# layer-1 weight conversion fillers re-partitioned over three split barriers instead of five
# baseline (speedup 1.0000x reference)
; __global__ void __launch_bounds__(512, 2) mk_fwd(Args args) {
;     ...
;     constexpr int I_IN = 32 * 120, I_O = 32 * 32, I_PE = 4 * 32, I_L = I_IN + 2 * I_O + I_PE;
.LBB0_160:
	s_or_b64 exec, exec, s[0:1]
	v_mov_b32_e32 v0, v252
	s_lshl_b32 s14, s96, 3
	v_readfirstlane_b32 s0, v0
	s_ashr_i32 s2, s0, 6
	s_add_i32 s3, s14, s2
	s_lshl_b32 s0, s86, 3
	s_add_i32 s15, s3, 0x1780
	v_writelane_b32 v253, s0, 34
	s_mov_b64 s[0:1], s[20:21]
	s_cmpk_gt_i32 s15, 0x1f54
	s_cbranch_scc1 .LBB0_209
	s_add_u32 s24, s0, 0x200000
	s_addc_u32 s25, s1, 0
	s_add_u32 s26, s0, 0x3e00000
	s_addc_u32 s27, s1, 0
	s_add_u32 s28, s0, 0x4e00000
	s_addc_u32 s29, s1, 0
	s_add_u32 s30, s0, 0x5e00000
	s_addc_u32 s31, s1, 0
	s_add_u32 s34, s0, 0x10000
	s_addc_u32 s35, s1, 0
	v_and_b32_e32 v2, 63, v0
	v_bfe_u32 v80, v0, 4, 2
	v_bfe_u32 v82, v0, 3, 3
	v_lshlrev_b32_e32 v0, 3, v0
	s_add_u32 s37, s0, 0x14000
	s_mulk_i32 s2, 0x4100
	v_lshlrev_b32_e32 v68, 2, v2
	v_and_b32_e32 v0, 56, v0
	s_addc_u32 s38, s1, 0
	s_add_i32 s2, s2, 0
	v_and_b32_e32 v4, 60, v68
	v_mul_u32_u24_e32 v3, 0x104, v0
	v_lshlrev_b32_e32 v5, 2, v82
	v_readlane_b32 s40, v253, 18
	v_lshl_add_u32 v1, v4, 2, s2
	s_movk_i32 s0, 0x104
	v_add3_u32 v83, s2, v3, v5
	v_readlane_b32 s50, v253, 28
	v_readlane_b32 s51, v253, 29
	v_or_b32_e32 v3, 4, v80
	v_mov_b32_e32 v69, 0
	v_mad_u32_u24 v81, v80, s0, v1
	v_readlane_b32 s41, v253, 19
	v_readlane_b32 s42, v253, 20
	v_readlane_b32 s43, v253, 21
	v_readlane_b32 s44, v253, 22
	v_readlane_b32 s45, v253, 23
	v_readlane_b32 s46, v253, 24
	v_readlane_b32 s47, v253, 25
	v_readlane_b32 s48, v253, 26
	v_readlane_b32 s49, v253, 27
	v_readlane_b32 s52, v253, 30
	v_readlane_b32 s53, v253, 31
	v_readlane_b32 s54, v253, 32
	v_readlane_b32 s55, v253, 33
	s_cmp_lg_u64 s[50:51], 0
	v_mul_u32_u24_e32 v3, 0x104, v3
	v_or_b32_e32 v84, 8, v82
	v_or_b32_e32 v85, 16, v82
	v_or_b32_e32 v86, 24, v82
	v_or_b32_e32 v87, 32, v82
	v_or_b32_e32 v88, 40, v82
	v_or_b32_e32 v89, 48, v82
	v_or_b32_e32 v90, 56, v82
	s_cselect_b64 s[0:1], -1, 0
	v_add_u32_e32 v91, s2, v68
	v_lshl_add_u64 v[70:71], s[16:17], 0, v[68:69]
	s_mov_b32 s39, 0x8000
	s_mov_b32 s40, 0x10000
	s_mov_b32 s41, 0x18000
	s_mov_b32 s42, 0x20000
	s_mov_b32 s43, 0x28000
	s_mov_b32 s44, 0x30000
	s_mov_b32 s45, 0x38000
	s_mov_b32 s46, 0x40000
	s_mov_b32 s47, 0x48000
	s_mov_b32 s48, 0x50000
	s_mov_b32 s49, 0x58000
	s_mov_b32 s50, 0x60000
	s_mov_b32 s51, 0x68000
	s_mov_b32 s52, 0x70000
	s_mov_b32 s53, 0x78000
	v_add_u32_e32 v92, 0x410, v81
	v_add_u32_e32 v93, 0x418, v81
	v_add_u32_e32 v94, 0x820, v81
	v_add_u32_e32 v95, 0x828, v81
	v_add_u32_e32 v96, 0xc30, v81
	v_add_u32_e32 v97, 0xc38, v81
	v_add_u32_e32 v98, 0x1040, v81
	v_add_u32_e32 v99, 0x1048, v81
	v_add_u32_e32 v100, 0x1450, v81
	v_add_u32_e32 v101, 0x1458, v81
	v_add_u32_e32 v102, 0x1860, v81
	v_add_u32_e32 v103, 0x1868, v81
	v_add_u32_e32 v104, 0x1c70, v81
	v_add_u32_e32 v105, 0x1c78, v81
	v_add_u32_e32 v106, 0x2080, v81
	v_add_u32_e32 v107, 0x2088, v81
	v_add_u32_e32 v108, 0x2490, v81
	v_add_u32_e32 v109, 0x2498, v81
	v_add_u32_e32 v110, 0x28a0, v81
	v_add_u32_e32 v111, 0x28a8, v81
	v_add_u32_e32 v112, 0x2cb0, v81
	v_add_u32_e32 v113, 0x2cb8, v81
	v_add_u32_e32 v114, 0x30c0, v81
	v_add_u32_e32 v115, 0x30c8, v81
	v_add_u32_e32 v116, 0x34d0, v81
	v_add_u32_e32 v117, 0x34d8, v81
	v_add_u32_e32 v118, 0x38e0, v81
	v_add_u32_e32 v119, 0x38e8, v81
	v_add_u32_e32 v120, 0x3cf0, v81
	v_lshlrev_b32_e32 v72, 2, v2
	s_mov_b32 s54, 0xf0000
	s_mov_b32 s55, 0x10e000
	s_mov_b32 s56, 0x12c000
	s_mov_b32 s57, 0x14a000
	s_mov_b32 s58, 0x168000
	s_mov_b32 s59, 0x186000
	s_mov_b32 s60, 0x1a4000
	s_mov_b32 s61, 0x1c2000
	v_lshlrev_b32_e32 v68, 2, v4
	v_add_u32_e32 v121, 0x3cf8, v81
	v_lshlrev_b32_e32 v74, 1, v0
	v_add_u32_e32 v122, v1, v3
	s_branch .LBB0_163
.LBB0_162:
	v_readlane_b32 s2, v253, 34
	s_add_i32 s15, s15, s2
	s_cmpk_gt_i32 s15, 0x1f54
	s_cbranch_scc1 .LBB0_209

; #define LAS __attribute__((address_space(3)))
; __global__ void __launch_bounds__(512, 2) mk_fwd(Args args) {
;     extern __shared__ __attribute__((aligned(16))) unsigned char lds[];
;     cg::grid_group grid = cg::this_grid();
;     const int G = gridDim.x, wg = blockIdx.x;
;     volatile LAS unsigned* MISC = (volatile LAS unsigned*)((LAS unsigned char*)lds + (LDS_BYTES - 64));
;     if (threadIdx.x < 16) MISC[threadIdx.x] = 0u;
;     __syncthreads();
;     XcdBarrier xbar = xcd_barrier_post((unsigned*)args.ws, MISC);
;     ...
;     const int lo = args.ph_lo, hi = args.ph_hi;
;     ...
;     if (lo < 0) grid.sync();
.LBB0_248:
	s_cmpk_lt_i32 s96, 0x380
	s_cselect_b64 s[2:3], -1, 0
	v_writelane_b32 v253, s2, 35
	s_ashr_i32 s97, s96, 31
	s_lshr_b32 s1, s97, 29
	v_writelane_b32 v253, s3, 36
	s_add_i32 s3, s96, 0x80
	s_ashr_i32 s4, s3, 31
	s_lshr_b32 s4, s4, 24
	s_add_i32 s2, s96, s1
	s_add_i32 s4, s3, s4
	s_ashr_i32 s1, s2, 3
	s_and_b32 s2, s2, -8
	s_and_b32 s4, s4, 0xffffff00
	s_mul_i32 s0, s87, s86
	s_sub_i32 s2, s96, s2
	s_ashr_i32 s87, s86, 31
	s_sub_i32 s3, s3, s4
	s_add_i32 s4, s96, 0xffffff40
	s_cmpk_gt_i32 s96, 0xbf
	s_cselect_b32 s4, s4, 0x100000
	s_cmpk_eq_i32 s86, 0x100
	s_cselect_b32 s5, s3, s96
	s_cselect_b32 s9, 64, s86
	s_cselect_b32 s8, s4, s96
	s_cmp_lt_i32 s5, 64
	s_cselect_b64 s[6:7], -1, 0
	v_writelane_b32 v253, s6, 37
	s_ashr_i32 s3, s5, 31
	s_mul_i32 s0, s0, s33
	v_writelane_b32 v253, s7, 38
	v_writelane_b32 v253, s3, 39
	s_lshr_b32 s3, s3, 29
	s_add_i32 s3, s5, s3
	s_ashr_i32 s4, s3, 3
	s_and_b32 s3, s3, -8
	s_sub_i32 s3, s5, s3
	v_writelane_b32 v253, s5, 40
	s_lshl_b32 s5, s3, 3
	s_cmpk_lt_i32 s8, 0x100
	s_cselect_b64 s[6:7], -1, 0
	v_writelane_b32 v253, s6, 41
	s_mov_b32 s29, 0
	v_mov_b32_e32 v169, 0
	v_writelane_b32 v253, s7, 42
	s_ashr_i32 s6, s8, 31
	v_writelane_b32 v253, s6, 43
	s_lshr_b32 s6, s6, 29
	s_add_i32 s6, s8, s6
	s_ashr_i32 s7, s6, 3
	s_and_b32 s6, s6, -8
	v_writelane_b32 v253, s8, 44
	s_sub_i32 s6, s8, s6
	s_lshl_b32 s8, s6, 5
	v_writelane_b32 v253, s9, 45
	s_ashr_i32 s9, s9, 31
	s_add_u32 s10, s20, 0x200
	v_writelane_b32 v253, s9, 46
	s_addc_u32 s11, s21, 0
	v_writelane_b32 v253, s10, 47
	v_mov_b32_e32 v214, 1
	v_mov_b32_e32 v215, 0x358637bd
	v_writelane_b32 v253, s11, 48
	s_add_u32 s10, s20, 0x1000
	s_addc_u32 s11, s21, 0
	v_writelane_b32 v253, s10, 49
	v_mov_b32_e32 v216, 0xbdd2d3e7
	v_mov_b64_e32 v[170:171], 0x100
	v_writelane_b32 v253, s11, 50
	s_add_u32 s10, s20, 0x1100
	s_addc_u32 s11, s21, 0
	v_writelane_b32 v253, s10, 51
	v_mov_b64_e32 v[172:173], 0xff
	v_mov_b32_e32 v217, 0x3c00
	v_writelane_b32 v253, s11, 52
	s_add_u32 s10, s20, 0x1200
	s_addc_u32 s11, s21, 0
	v_writelane_b32 v253, s10, 53
	v_mov_b32_e32 v218, 0x42a00000
	v_mov_b32_e32 v219, 0x7f800000
	v_writelane_b32 v253, s11, 54
	s_add_u32 s10, s20, 0x1300
	s_addc_u32 s11, s21, 0
	v_writelane_b32 v253, s10, 55
	s_cmp_eq_u32 s36, 15
	v_mov_b32_e32 v220, 0x2800
	v_writelane_b32 v253, s11, 56
	s_cselect_b64 s[10:11], -1, 0
	v_writelane_b32 v253, s10, 57
	s_cmp_eq_u32 s36, 14
	v_mov_b32_e32 v221, 0xff800000
	v_writelane_b32 v253, s11, 58
	s_cselect_b64 s[10:11], -1, 0
	v_writelane_b32 v253, s10, 59
	s_cmp_eq_u32 s36, 13
	v_mov_b32_e32 v222, 0xf0000
	v_writelane_b32 v253, s11, 60
	s_cselect_b64 s[10:11], -1, 0
	v_writelane_b32 v253, s10, 61
	s_cmp_eq_u32 s36, 12
	s_movk_i32 s69, 0x2000
	v_writelane_b32 v253, s11, 62
	s_cselect_b64 s[10:11], -1, 0
	v_writelane_b32 v253, s10, 63
	s_cmp_eq_u32 s36, 11
	s_mov_b32 s88, 0x10000
	v_writelane_b32 v254, s11, 0
	s_cselect_b64 s[10:11], -1, 0
	v_writelane_b32 v254, s10, 1
	s_cmp_eq_u32 s36, 10
	s_movk_i32 s89, 0x4000
	v_writelane_b32 v254, s11, 2
	s_cselect_b64 s[10:11], -1, 0
	v_writelane_b32 v254, s10, 3
	s_cmp_eq_u32 s36, 9
	s_movk_i32 s84, 0x6000
	v_writelane_b32 v254, s11, 4
	s_cselect_b64 s[10:11], -1, 0
	v_writelane_b32 v254, s10, 5
	s_cmp_eq_u32 s36, 8
	s_mov_b32 s85, 0x18000
	v_writelane_b32 v254, s11, 6
	s_cselect_b64 s[10:11], -1, 0
	v_writelane_b32 v254, s10, 7
	s_cmp_eq_u32 s36, 7
	s_mov_b32 s90, 0x8000
	v_writelane_b32 v254, s11, 8
	s_cselect_b64 s[10:11], -1, 0
	v_writelane_b32 v254, s10, 9
	s_cmp_eq_u32 s36, 6
	s_mov_b32 s70, 0xa000
	v_writelane_b32 v254, s11, 10
	s_cselect_b64 s[10:11], -1, 0
	v_writelane_b32 v254, s10, 11
	s_cmp_eq_u32 s36, 5
	s_mov_b32 s91, 0xc000
	v_writelane_b32 v254, s11, 12
	s_cselect_b64 s[10:11], -1, 0
	v_writelane_b32 v254, s10, 13
	s_cmp_eq_u32 s36, 4
	s_mov_b32 s71, 0xe000
	v_writelane_b32 v254, s11, 14
	s_cselect_b64 s[10:11], -1, 0
	v_writelane_b32 v254, s10, 15
	s_cmp_eq_u32 s36, 3
	s_movk_i32 s92, 0x1000
	v_writelane_b32 v254, s11, 16
	s_cselect_b64 s[10:11], -1, 0
	v_writelane_b32 v254, s10, 17
	s_cmp_eq_u32 s36, 2
	s_mov_b32 s72, 0x42a00000
	v_writelane_b32 v254, s11, 18
	s_cselect_b64 s[10:11], -1, 0
	v_writelane_b32 v254, s10, 19
	s_cmp_eq_u32 s36, 1
	s_mov_b32 s33, 0xff800000
	v_writelane_b32 v254, s11, 20
	s_cselect_b64 s[10:11], -1, 0
	v_writelane_b32 v254, s10, 21
	s_cmp_eq_u32 s36, 0
	s_mov_b32 s93, 0x800000
	v_writelane_b32 v254, s11, 22
	s_cselect_b64 s[10:11], -1, 0
	s_lshl_b32 s9, s36, 8
	v_writelane_b32 v254, s10, 23
	s_add_u32 s9, s20, s9
	v_readlane_b32 s36, v253, 18
	v_writelane_b32 v254, s11, 24
	s_addc_u32 s10, s21, 0
	s_add_u32 s12, s9, 0x1400
	s_addc_u32 s13, s10, 0
	v_writelane_b32 v254, s12, 25
	v_readlane_b32 s46, v253, 28
	v_readlane_b32 s47, v253, 29
	v_writelane_b32 v254, s13, 26
	s_add_u32 s12, s20, 0x3500
	s_addc_u32 s13, s21, 0
	v_writelane_b32 v254, s12, 27
	s_mov_b64 s[74:75], 0x80000
	s_mov_b64 s[30:31], 0x80
	v_writelane_b32 v254, s13, 28
	s_add_u32 s12, s20, 0x3400
	s_addc_u32 s13, s21, 0
	v_writelane_b32 v254, s12, 29
	s_mov_b64 s[34:35], 0xf0000
	v_readlane_b32 s37, v253, 19
	v_writelane_b32 v254, s13, 30
	s_add_u32 s12, s9, 0x2400
	s_addc_u32 s13, s10, 0
	v_writelane_b32 v254, s12, 31
	s_add_i32 s9, s14, 0x1f55
	s_cmp_lg_u64 s[46:47], 0
	v_writelane_b32 v254, s13, 32
	v_writelane_b32 v254, s9, 33
	s_cselect_b64 s[10:11], -1, 0
	v_writelane_b32 v254, s10, 34
	s_cmpk_lt_i32 s96, 0x100
	v_readlane_b32 s38, v253, 20
	v_writelane_b32 v254, s11, 35
	s_cselect_b64 s[10:11], -1, 0
	v_writelane_b32 v254, s10, 36
	s_lshl_b32 s9, s96, 9
	v_readlane_b32 s39, v253, 21
	v_writelane_b32 v254, s11, 37
	v_writelane_b32 v254, s9, 38
; #define PG8_LAS __attribute__((address_space(3)))
;     __host__ __device__ void init(int M, int N, int G_, int c_, int skip0_, int nskip_) { S.init(M, N - nskip_ * BM, G_, c_); skip0 = skip0_; nskip = nskip_; }
; __global__ void __launch_bounds__(512, 2) mk_fwd(Args args) {
;     ...
;         FILL_SEAM(p1, 1280, 2560, 0, 0);
;         if (IN(p1 + 1)) {
;             if(!(DIS&1)) { PTRS(); hgrn_pass1(H, args.in[4], l, US, DD, (char*)lds, wg, G); }
;             xcd_barrier_arrive(xbar);
;             if(!(DIS&8)) { PTRS(); mix_attn(H, VT, args.in[6] + l * 256, l, args.in[7] + l * GW, YC, (char*)lds, wg, G); }
;             xcd_barrier_wait(xbar);
;             { TIDS(); PTRS(); hgrn_scan(US, DD, SB, gtid, gstride); }
;             xcd_barrier_arrive(xbar);
;             if(!(DIS&2)) { PTRS(); mix_sgu(H, args.in[8] + l * GW, args.in[9] + l * GW, args.in[10] + (size_t)l * 4 * 16384, args.in[11] + l * GW, YC, (char*)lds, wg, G); }
;             if(!(DIS&4)) { TIDS(); PTRS(); mix_conv(H, args.in[3] + l * 3 * GW, YC, gtid, gstride); }
;             xcd_barrier_wait(xbar);
;         }
;         if (IN(p1 + 3)) { PTRS(); hgrn_pass3(H, args.in[4], l, SB, args.in[5] + l * GW, YC, (char*)lds, wg, G); }
;         FILL_SEAM(p1 + 3, 2560, I_IN, I_IN + 2 * I_O, I_L);
;         if (IN(p1 + 4) && !(DIS&16)) { PTRS(); const float* xres = (l == 0) ? args.in[0] : XF; asm volatile("" : "+s"(xres));
;             pg8::Gemm g{YC, WoutT + (size_t)l * DM * DM, MT, DM, DM}; pg8::StaticOrder S; S.init(MT, DM, G, wg); pg8::EpiZ E{xres, Z, XLNB, STATS + (size_t)l * MT * 2, DM, ALPHA};
;             pg8::gemm_phase<pg8::EpiZ, pg8::StaticOrder, true, true>((PG8_LAS unsigned char*)lds, g, S, E);
;         }
;         FILL_SEAM(p1 + 4, I_IN, I_IN + I_O, 0, 0);
;         if (IN(p1 + 5) && !(DIS&32)) { PTRS(); float* xout = (l == DEPTH - 1) ? args.out : XF; asm volatile("" : "+s"(xout));
;             pg8::Gemm g{XLNB, WpgT + (size_t)l * DM * DM, MT, DM, DM}; pg8::StaticOrder S; S.init(MT, DM, G, wg); pg8::EpiPG E{XLNB, STATS + (size_t)l * MT * 2, C1 + l * DM, C2 + l * DM, args.in[13] + l * DM, args.in[14] + l * DM, PE, xout, (l == DEPTH - 1) ? (bf16*)nullptr : XB, DM};
;             pg8::gemm_phase<pg8::EpiPG, pg8::StaticOrder, true, true>((PG8_LAS unsigned char*)lds, g, S, E);
;         }
;         if (l + 1 < DEPTH) FILL_SEAM(p1 + 5, I_IN + I_O, I_IN + 2 * I_O, 0, 0);
	s_lshl_b32 s9, s86, 9
	s_cmpk_lt_i32 s96, 0x200
	v_writelane_b32 v254, s9, 39
	s_cselect_b64 s[10:11], -1, 0
	v_writelane_b32 v254, s10, 40
	s_add_i32 s9, s14, 0x272a
	v_readlane_b32 s40, v253, 22
	v_writelane_b32 v254, s11, 41
	v_writelane_b32 v254, s9, 42
	s_add_i32 s9, s14, 0x2f00
	v_writelane_b32 v254, s9, 43
	s_lshl_b32 s9, s2, 5
	s_add_i32 s10, s14, 0x2a80
	s_cmp_gt_i32 s23, 7
	v_writelane_b32 v254, s10, 44
	s_cselect_b64 s[10:11], -1, 0
	v_writelane_b32 v254, s10, 45
	v_readlane_b32 s41, v253, 23
	v_readlane_b32 s42, v253, 24
	v_writelane_b32 v254, s11, 46
	s_add_i32 s10, s14, 0x2e80
	v_writelane_b32 v254, s10, 47
	s_cmp_lt_i32 s2, 0
	s_movk_i32 s10, 0x71
	s_cselect_b32 s10, s10, 0x70
	s_mul_i32 s10, s2, s10
	s_mul_i32 s2, s2, 33
	s_cselect_b32 s2, s2, s9
	s_add_i32 s10, s10, s1
	s_mul_hi_i32 s9, s10, 0x92492493
	s_add_i32 s9, s9, s10
	s_lshr_b32 s11, s9, 31
	s_ashr_i32 s9, s9, 7
	s_add_i32 s9, s9, s11
	s_mul_i32 s11, s9, 0xe0
	s_sub_i32 s10, s10, s11
	s_bfe_u32 s11, s10, 0x3001c
	s_add_i32 s11, s10, s11
	s_sext_i32_i16 s12, s11
	s_and_b32 s11, s11, 0xfff8
	s_sub_i32 s11, s10, s11
	s_lshl_b32 s9, s9, 3
	s_sext_i32_i16 s11, s11
	s_add_i32 s14, s9, s11
	s_ashr_i32 s9, s12, 3
	s_add_i32 s11, s9, 2
	s_cmpk_lt_i32 s10, 0x80
	s_cselect_b32 s12, s9, s11
	s_cmp_lt_i32 s3, 0
	s_mul_i32 s3, s3, 9
	s_cselect_b32 s3, s3, s5
	s_add_i32 s3, s3, s4
	s_ashr_i32 s4, s3, 31
	s_lshr_b32 s4, s4, 24
	s_add_i32 s4, s3, s4
	s_and_b32 s5, s4, 0xffffff00
	s_sub_i32 s5, s3, s5
	s_ashr_i32 s3, s4, 8
	s_lshl_b32 s4, s3, 3
	s_sub_i32 s3, 2, s4
	s_min_u32 s9, s3, 8
	s_cmp_lt_i32 s6, 0
	s_mul_i32 s6, s6, 33
	s_cselect_b32 s3, s6, s8
	s_add_i32 s3, s3, s7
	s_ashr_i32 s6, s3, 31
	s_lshr_b32 s6, s6, 26
	s_add_i32 s6, s3, s6
	s_and_b32 s7, s6, 0xffc0
	s_sub_i32 s3, s3, s7
	s_bfe_i32 s7, s3, 0x80000
	s_bfe_u32 s7, s7, 0x3000c
	s_add_i32 s1, s2, s1
	s_add_i32 s7, s3, s7
	s_ashr_i32 s2, s1, 31
	s_and_b32 s8, s7, 0xf8
	s_lshr_b32 s2, s2, 26
	s_sub_i32 s3, s3, s8
	s_add_i32 s8, s1, s2
	s_and_b32 s2, s8, 0xffc0
	s_sub_i32 s1, s1, s2
	s_bfe_i32 s2, s1, 0x80000
	s_bfe_u32 s2, s2, 0x3000c
	s_add_i32 s10, s1, s2
	s_and_b32 s2, s10, 0xf8
	s_sub_i32 s1, s1, s2
	s_ashr_i32 s2, s6, 6
	s_bfe_i32 s6, s7, 0x80000
	s_lshl_b32 s2, s2, 3
	s_sext_i32_i16 s6, s6
	s_sext_i32_i8 s3, s3
	s_add_i32 s24, s2, s3
	s_ashr_i32 s2, s6, 3
	v_writelane_b32 v254, s2, 48
	s_lshr_b32 s2, s6, 3
	s_bfe_i64 s[2:3], s[2:3], 0x100000
	s_lshl_b64 s[2:3], s[2:3], 17
	v_writelane_b32 v254, s2, 49
	s_sext_i32_i8 s1, s1
	s_ashr_i32 s25, s24, 31
	v_writelane_b32 v254, s3, 50
	s_ashr_i32 s2, s8, 6
	s_bfe_i32 s3, s10, 0x80000
	s_lshl_b32 s2, s2, 3
	s_sext_i32_i16 s3, s3
	s_add_i32 s6, s2, s1
	s_lshr_b32 s2, s3, 3
	s_ashr_i32 s1, s3, 3
	s_bfe_i64 s[2:3], s[2:3], 0x100000
	v_writelane_b32 v254, s1, 51
	s_lshl_b64 s[2:3], s[2:3], 20
	v_writelane_b32 v254, s2, 52
	s_ashr_i32 s15, s14, 31
	v_cvt_f32_ubyte0_e32 v1, s9
	v_writelane_b32 v254, s3, 53
	s_mov_b32 s2, s24
	v_writelane_b32 v254, s2, 54
	s_ashr_i32 s13, s12, 31
	v_cvt_f32_i32_e32 v0, s5
	v_writelane_b32 v254, s3, 55
	s_lshl_b64 s[2:3], s[24:25], 17
	v_writelane_b32 v254, s2, 56
	v_rcp_iflag_f32_e32 v2, v1
	s_ashr_i32 s7, s6, 31
	v_writelane_b32 v254, s3, 57
	s_mov_b32 s2, s14
	v_writelane_b32 v254, s2, 58
	v_mul_f32_e32 v2, v0, v2
	v_trunc_f32_e32 v2, v2
	v_writelane_b32 v254, s3, 59
	s_lshl_b64 s[2:3], s[14:15], 20
	v_writelane_b32 v254, s2, 60
	v_fma_f32 v0, -v2, v1, v0
	s_ashr_i32 s1, s5, 30
	v_writelane_b32 v254, s3, 61
	s_mov_b32 s2, s12
	v_writelane_b32 v254, s2, 62
	s_or_b32 s1, s1, 1
	s_mov_b32 s11, 0xc2a00000
	v_writelane_b32 v254, s3, 63
	s_lshl_b64 s[2:3], s[12:13], 20
	v_writelane_b32 v255, s2, 0
	s_movk_i32 s13, 0x3c00
	s_mov_b32 s10, 0x3e38aa3b
	v_writelane_b32 v255, s3, 1
	s_mov_b32 s2, s6
	v_writelane_b32 v255, s2, 2
	s_mov_b32 s12, 0x3fb504f3
	v_readlane_b32 s43, v253, 25
	v_writelane_b32 v255, s3, 3
	s_lshl_b64 s[2:3], s[6:7], 20
	v_writelane_b32 v255, s2, 4
	v_readlane_b32 s44, v253, 26
	v_readlane_b32 s45, v253, 27
	v_writelane_b32 v255, s3, 5
	v_cmp_ge_f32_e64 s[2:3], |v0|, v1
	v_cvt_i32_f32_e32 v0, v2
	s_and_b64 s[2:3], s[2:3], exec
	v_writelane_b32 v255, s0, 6
	s_cselect_b32 s0, s1, 0
	v_readfirstlane_b32 s1, v0
	s_add_i32 s0, s1, s0
	s_mul_i32 s1, s0, s9
	s_sub_i32 s1, s5, s1
	s_sext_i32_i16 s1, s1
	s_add_i32 s2, s4, s1
	s_sext_i32_i16 s1, s0
	v_writelane_b32 v255, s1, 7
	s_bfe_i64 s[0:1], s[0:1], 0x100000
	s_lshl_b64 s[0:1], s[0:1], 20
	v_writelane_b32 v255, s0, 8
	s_ashr_i32 s3, s2, 31
	v_mbcnt_lo_u32_b32 v0, -1, 0
	v_writelane_b32 v255, s1, 9
	s_lshl_b32 s0, s96, 8
	v_writelane_b32 v255, s0, 10
	s_lshl_b32 s0, s86, 8
	v_writelane_b32 v255, s0, 11
	s_lshl_b32 s0, s96, 1
	v_writelane_b32 v255, s0, 12
	s_lshl_b32 s0, s86, 1
	v_writelane_b32 v255, s0, 13
	s_lshl_b32 s0, s96, 2
	v_writelane_b32 v255, s0, 14
	s_lshl_b32 s0, s86, 2
	v_writelane_b32 v255, s0, 15
	s_lshl_b32 s0, s96, 7
	v_writelane_b32 v255, s0, 16
	s_lshl_b32 s0, s86, 7
	v_writelane_b32 v255, s0, 17
	s_lshl_b32 s0, s96, 10
	v_writelane_b32 v255, s0, 18
	s_lshl_b32 s0, s86, 10
	v_writelane_b32 v255, s0, 19
	s_lshl_b32 s0, s96, 12
	v_writelane_b32 v255, s0, 20
	s_lshl_b32 s0, s86, 12
	v_writelane_b32 v255, s0, 21
	s_lshl_b32 s0, s96, 6
	v_writelane_b32 v255, s0, 22
	s_lshl_b32 s0, s86, 6
	v_writelane_b32 v255, s0, 23
	s_add_i32 s0, 0, 0x23fc0
	v_writelane_b32 v255, s0, 24
	s_add_i32 s0, 0, 0x23fc4
	v_writelane_b32 v255, s0, 25
	s_add_i32 s0, 0, 0x23fc8
	v_writelane_b32 v255, s0, 26
	s_add_i32 s0, 0, 0x23fcc
	v_writelane_b32 v255, s0, 27
	s_add_i32 s0, 0, 0x23fd0
	v_writelane_b32 v255, s0, 28
	s_add_i32 s0, 0, 0x9000
	v_writelane_b32 v255, s0, 29
	s_add_i32 s0, 0, 0x1bc00
	v_writelane_b32 v255, s0, 30
	s_add_i32 s0, 0, 0x14400
	v_writelane_b32 v255, s0, 31
	s_add_i32 s0, 0, 0x19400
	v_writelane_b32 v255, s0, 32
	s_mov_b32 s0, s2
	v_writelane_b32 v255, s0, 33
	v_mbcnt_hi_u32_b32 v223, -1, v0
	s_mov_b64 s[8:9], 0
	v_writelane_b32 v255, s1, 34
	s_lshl_b64 s[0:1], s[2:3], 20
	v_writelane_b32 v255, s0, 35
	s_mov_b32 s2, s29
	v_readlane_b32 s48, v253, 30
	v_writelane_b32 v255, s1, 36
	s_lshl_b64 s[0:1], s[96:97], 15
	v_writelane_b32 v255, s0, 37
	v_readlane_b32 s49, v253, 31
	v_readlane_b32 s50, v253, 32
	v_writelane_b32 v255, s1, 38
	s_lshl_b64 s[0:1], s[86:87], 15
	v_writelane_b32 v255, s0, 39
	v_readlane_b32 s51, v253, 33
	s_nop 0
	v_writelane_b32 v255, s1, 40
	s_mov_b64 s[0:1], -1
	v_writelane_b32 v255, s0, 41
	s_nop 1
	v_writelane_b32 v255, s1, 42
	v_writelane_b32 v255, s96, 43
	s_nop 1
	v_writelane_b32 v255, s97, 44
	s_branch .LBB0_253

.LBB0_427:
	s_or_b64 exec, exec, s[0:1]
	v_mov_b32_e32 v0, v252
	v_readlane_b32 s3, v254, 33
	v_readfirstlane_b32 s0, v0
	s_ashr_i32 s2, s0, 6
	s_add_i32 s26, s3, s2
	s_mov_b64 s[0:1], s[20:21]
	s_cmpk_gt_i32 s26, 0x2729
	s_cbranch_scc1 .LBB0_476
	s_add_u32 s27, s0, 0x200000
	s_addc_u32 s36, s1, 0
	s_add_u32 s37, s0, 0x3e00000
	s_addc_u32 s38, s1, 0
	s_add_u32 s39, s0, 0x4e00000
	s_addc_u32 s40, s1, 0
	s_add_u32 s41, s0, 0x5e00000
	s_addc_u32 s42, s1, 0
	s_add_u32 s43, s0, 0x10000
	s_addc_u32 s44, s1, 0
	v_and_b32_e32 v2, 63, v0
	v_bfe_u32 v69, v0, 4, 2
	v_bfe_u32 v80, v0, 3, 3
	v_lshlrev_b32_e32 v0, 3, v0
	s_add_u32 s45, s0, 0x14000
	s_mulk_i32 s2, 0x4100
	v_and_b32_e32 v70, 56, v0
	s_addc_u32 s46, s1, 0
	s_add_i32 s0, s2, 0
	v_lshlrev_b32_e32 v168, 2, v2
	v_mul_u32_u24_e32 v0, 0x104, v70
	v_lshlrev_b32_e32 v3, 2, v80
	v_and_b32_e32 v68, 60, v168
	v_add3_u32 v81, s0, v0, v3
	v_or_b32_e32 v0, 4, v69
	v_lshl_add_u32 v1, v68, 2, s0
	s_movk_i32 s1, 0x104
	v_mul_u32_u24_e32 v0, 0x104, v0
	v_mad_u32_u24 v71, v69, s1, v1
	v_or_b32_e32 v82, 8, v80
	v_or_b32_e32 v83, 16, v80
	v_or_b32_e32 v84, 24, v80
	v_or_b32_e32 v85, 32, v80
	v_or_b32_e32 v86, 40, v80
	v_or_b32_e32 v87, 48, v80
	v_or_b32_e32 v88, 56, v80
	v_add_u32_e32 v89, s0, v168
	v_lshl_add_u64 v[72:73], s[16:17], 0, v[168:169]
	v_lshlrev_b32_e32 v74, 2, v2
	v_add_u32_e32 v90, v1, v0
	s_branch .LBB0_430
.LBB0_429:
	v_readlane_b32 s0, v253, 34
	s_add_i32 s26, s26, s0
	s_cmpk_gt_i32 s26, 0x2729
	s_cbranch_scc1 .LBB0_476

; #define LDS_WAIT() asm volatile("s_waitcnt lgkmcnt(0)" ::: "memory")
; __device__ __forceinline__ unsigned pk2(float lo, float hi) { unsigned r; asm("v_cvt_pk_bf16_f32 %0, %1, %2" : "=v"(r) : "v"(lo), "v"(hi)); return r; }
; __device__ __forceinline__ void p0_transpose_item(const float* W, int K, int N, bf16* WT, float* scr, int item, int lane, const float* scale, const float* cb, float* c1, float* c2) {
;     const int nblk = N / 64, kb = item / nblk, nb = item % nblk, k0 = 64 * kb, n0 = 64 * nb;
;     const int lr = lane >> 4, lc = (lane & 15) * 4;
;     f32x4 v[16];
; #pragma unroll
;     for (int i = 0; i < 16; ++i) v[i] = *(const f32x4*)(W + (size_t)(k0 + 4 * i + lr) * N + n0 + lc);
; #pragma unroll
;     for (int i = 0; i < 16; ++i) { const int kk = 4 * i + lr; f32x4 w = v[i]; if (scale) w = w * scale[k0 + kk]; float* d = scr + kk * 65 + lc; d[0] = w[0]; d[1] = w[1]; d[2] = w[2]; d[3] = w[3]; }
;     LDS_WAIT(); asm volatile("" ::: "memory");
;     const int c = lane & 7;
; #pragma unroll
;     for (int j = 0; j < 8; ++j) { const int n = (lane >> 3) + 8 * j; const float* sp = scr + (8 * c) * 65 + n;
;         v4u o; o.x = pk2(sp[0 * 65], sp[1 * 65]); o.y = pk2(sp[2 * 65], sp[3 * 65]); o.z = pk2(sp[4 * 65], sp[5 * 65]); o.w = pk2(sp[6 * 65], sp[7 * 65]);
;         *(v4u*)(WT + (size_t)(n0 + n) * K + k0 + 8 * c) = o; }
; __global__ void __launch_bounds__(512, 2) mk_fwd(Args args) {
;     ...
;     constexpr int I_IN = 32 * 120, I_O = 32 * 32, I_PE = 4 * 32, I_L = I_IN + 2 * I_O + I_PE;
.LBB0_980:
	s_or_b64 exec, exec, s[0:1]
	v_mov_b32_e32 v0, v252
	v_readlane_b32 s3, v254, 42
	v_readfirstlane_b32 s0, v0
	s_ashr_i32 s2, s0, 6
	s_add_i32 s24, s3, s2
	s_mov_b64 s[0:1], s[20:21]
	s_cmpk_gt_i32 s24, 0x2eff
	s_cbranch_scc1 .LBB0_1029
	s_add_u32 s25, s0, 0x200000
	s_addc_u32 s26, s1, 0
	s_add_u32 s27, s0, 0x3e00000
	s_addc_u32 s36, s1, 0
	s_add_u32 s37, s0, 0x4e00000
	s_addc_u32 s38, s1, 0
	s_add_u32 s39, s0, 0x5e00000
	s_addc_u32 s40, s1, 0
	s_add_u32 s41, s0, 0x10000
	s_addc_u32 s42, s1, 0
	v_and_b32_e32 v2, 63, v0
	v_bfe_u32 v69, v0, 4, 2
	v_bfe_u32 v80, v0, 3, 3
	v_lshlrev_b32_e32 v0, 3, v0
	s_add_u32 s43, s0, 0x14000
	s_mulk_i32 s2, 0x4100
	v_and_b32_e32 v70, 56, v0
	s_addc_u32 s44, s1, 0
	s_add_i32 s0, s2, 0
	v_lshlrev_b32_e32 v168, 2, v2
	v_mul_u32_u24_e32 v0, 0x104, v70
	v_lshlrev_b32_e32 v3, 2, v80
	v_and_b32_e32 v68, 60, v168
	v_add3_u32 v81, s0, v0, v3
	v_or_b32_e32 v0, 4, v69
	v_lshl_add_u32 v1, v68, 2, s0
	s_movk_i32 s1, 0x104
	v_mul_u32_u24_e32 v0, 0x104, v0
	v_mad_u32_u24 v71, v69, s1, v1
	v_or_b32_e32 v82, 8, v80
	v_or_b32_e32 v83, 16, v80
	v_or_b32_e32 v84, 24, v80
	v_or_b32_e32 v85, 32, v80
	v_or_b32_e32 v86, 40, v80
	v_or_b32_e32 v87, 48, v80
	v_or_b32_e32 v88, 56, v80
	v_add_u32_e32 v89, s0, v168
	v_lshl_add_u64 v[72:73], s[16:17], 0, v[168:169]
	v_lshlrev_b32_e32 v74, 2, v2
	v_add_u32_e32 v90, v1, v0
	s_branch .LBB0_983
.LBB0_982:
	v_readlane_b32 s0, v253, 34
	s_add_i32 s24, s24, s0
	s_cmpk_gt_i32 s24, 0x2eff
	s_cbranch_scc1 .LBB0_1029
.LBB0_983:
	s_mul_hi_i32 s0, s24, 0xae4c415d
	s_add_i32 s0, s0, s24
	s_lshr_b32 s1, s0, 31
	s_ashr_i32 s0, s0, 12
	s_add_i32 s0, s0, s1
	s_mul_i32 s1, s0, 0x1780
	s_sub_i32 s45, s24, s1
	s_cmpk_gt_i32 s45, 0xeff
	s_mov_b64 s[2:3], -1
	s_cbranch_scc0 .LBB0_1019
	s_cmpk_gt_u32 s45, 0x12ff
	s_cbranch_scc0 .LBB0_1016
	s_ashr_i32 s1, s0, 31
	s_cmpk_gt_u32 s45, 0x16ff
	s_cbranch_scc0 .LBB0_987
	v_readlane_b32 s48, v253, 18
	s_lshl_b64 s[2:3], s[0:1], 21
	v_readlane_b32 s62, v253, 32
	v_readlane_b32 s63, v253, 33
	s_add_u32 s4, s62, s2
	s_addc_u32 s5, s63, s3
	s_lshl_b64 s[2:3], s[0:1], 20
	s_add_u32 s6, s39, s2
	s_addc_u32 s3, s40, s3
	s_lshl_b32 s2, s45, 1
	s_and_b32 s7, s2, 0x1c0
	s_lshl_b32 s2, s45, 6
	s_and_b32 s2, s2, 0x7c0
	s_lshl_b32 s8, s2, 2
	s_add_u32 s4, s4, s8
	v_or_b32_e32 v2, s7, v69
	s_addc_u32 s5, s5, 0
	v_lshlrev_b32_e32 v168, 2, v68
	v_lshl_add_u64 v[0:1], s[4:5], 0, v[168:169]
	v_lshlrev_b32_e32 v168, 13, v2
	v_lshl_add_u64 v[60:61], v[0:1], 0, v[168:169]
	v_add_co_u32_e32 v4, vcc, s90, v60
	s_mov_b32 s4, 0x20000
	s_nop 0
	v_addc_co_u32_e32 v5, vcc, 0, v61, vcc
	v_add_co_u32_e32 v8, vcc, s88, v60
	global_load_dwordx4 v[0:3], v[60:61], off
	s_nop 0
	global_load_dwordx4 v[4:7], v[4:5], off
	v_addc_co_u32_e32 v9, vcc, 0, v61, vcc
	v_add_co_u32_e32 v12, vcc, s85, v60
	v_lshlrev_b32_e32 v168, 1, v70
	s_nop 0
	v_addc_co_u32_e32 v13, vcc, 0, v61, vcc
	global_load_dwordx4 v[8:11], v[8:9], off
	s_nop 0
	global_load_dwordx4 v[12:15], v[12:13], off
	v_add_co_u32_e32 v16, vcc, s4, v60
	s_mov_b32 s4, 0x28000
	s_nop 0
	v_addc_co_u32_e32 v17, vcc, 0, v61, vcc
	v_add_co_u32_e32 v20, vcc, s4, v60
	s_mov_b32 s4, 0x30000
	s_nop 0
	v_addc_co_u32_e32 v21, vcc, 0, v61, vcc
	global_load_dwordx4 v[16:19], v[16:17], off
	s_nop 0
	global_load_dwordx4 v[20:23], v[20:21], off
	v_add_co_u32_e32 v24, vcc, s4, v60
	s_mov_b32 s4, 0x38000
	s_nop 0
	v_addc_co_u32_e32 v25, vcc, 0, v61, vcc
	v_add_co_u32_e32 v28, vcc, s4, v60
	s_mov_b32 s4, 0x40000
	s_nop 0
	v_addc_co_u32_e32 v29, vcc, 0, v61, vcc
	global_load_dwordx4 v[24:27], v[24:25], off
	s_nop 0
	global_load_dwordx4 v[28:31], v[28:29], off
	v_add_co_u32_e32 v32, vcc, s4, v60
	s_mov_b32 s4, 0x48000
	s_nop 0
	v_addc_co_u32_e32 v33, vcc, 0, v61, vcc
	v_add_co_u32_e32 v36, vcc, s4, v60
	s_mov_b32 s4, 0x50000
	s_nop 0
	v_addc_co_u32_e32 v37, vcc, 0, v61, vcc
	global_load_dwordx4 v[32:35], v[32:33], off
	s_nop 0
	global_load_dwordx4 v[36:39], v[36:37], off
	v_add_co_u32_e32 v40, vcc, s4, v60
	s_mov_b32 s4, 0x58000
	s_nop 0
	v_addc_co_u32_e32 v41, vcc, 0, v61, vcc
	v_add_co_u32_e32 v44, vcc, s4, v60
	s_mov_b32 s4, 0x60000
	s_nop 0
	v_addc_co_u32_e32 v45, vcc, 0, v61, vcc
	global_load_dwordx4 v[40:43], v[40:41], off
	s_nop 0
	global_load_dwordx4 v[44:47], v[44:45], off
	v_add_co_u32_e32 v48, vcc, s4, v60
	s_mov_b32 s4, 0x68000
	s_nop 0
	v_addc_co_u32_e32 v49, vcc, 0, v61, vcc
	global_load_dwordx4 v[48:51], v[48:49], off
	v_add_co_u32_e32 v52, vcc, s4, v60
	s_mov_b32 s4, 0x70000
	s_nop 0
	v_addc_co_u32_e32 v53, vcc, 0, v61, vcc
	global_load_dwordx4 v[52:55], v[52:53], off
	v_add_co_u32_e32 v56, vcc, s4, v60
	s_mov_b32 s4, 0x78000
	s_nop 0
	v_addc_co_u32_e32 v57, vcc, 0, v61, vcc
	global_load_dwordx4 v[56:59], v[56:57], off
	v_add_co_u32_e32 v60, vcc, s4, v60
	s_lshl_b32 s4, s7, 1
	s_nop 0
	v_addc_co_u32_e32 v61, vcc, 0, v61, vcc
	global_load_dwordx4 v[60:63], v[60:61], off
	s_waitcnt vmcnt(0)
	ds_write2_b32 v71, v0, v1 offset1:1
	ds_write2_b32 v71, v2, v3 offset0:2 offset1:3
	v_add_u32_e32 v0, 0x410, v71
	s_waitcnt vmcnt(14)
	ds_write2_b32 v0, v4, v5 offset1:1
	v_add_u32_e32 v0, 0x418, v71
	ds_write2_b32 v0, v6, v7 offset1:1
	v_add_u32_e32 v0, 0x820, v71
	s_add_u32 s4, s6, s4
	s_addc_u32 s5, s3, 0
	s_waitcnt vmcnt(13)
	ds_write2_b32 v0, v8, v9 offset1:1
	v_add_u32_e32 v0, 0x828, v71
	ds_write2_b32 v0, v10, v11 offset1:1
	v_add_u32_e32 v0, 0xc30, v71
	s_waitcnt vmcnt(12)
	ds_write2_b32 v0, v12, v13 offset1:1
	v_add_u32_e32 v0, 0xc38, v71
	ds_write2_b32 v0, v14, v15 offset1:1
	v_add_u32_e32 v0, 0x1040, v71
	v_lshl_add_u64 v[4:5], s[4:5], 0, v[168:169]
	v_readlane_b32 s49, v253, 19
	v_readlane_b32 s50, v253, 20
	s_waitcnt vmcnt(11)
; #define LDS_WAIT() asm volatile("s_waitcnt lgkmcnt(0)" ::: "memory")
; __device__ __forceinline__ unsigned pk2(float lo, float hi) { unsigned r; asm("v_cvt_pk_bf16_f32 %0, %1, %2" : "=v"(r) : "v"(lo), "v"(hi)); return r; }
; __device__ __forceinline__ void p0_transpose_item(const float* W, int K, int N, bf16* WT, float* scr, int item, int lane, const float* scale, const float* cb, float* c1, float* c2) {
;     ...
;     for (int i = 0; i < 16; ++i) v[i] = *(const f32x4*)(W + (size_t)(k0 + 4 * i + lr) * N + n0 + lc);
; #pragma unroll
;     for (int i = 0; i < 16; ++i) { const int kk = 4 * i + lr; f32x4 w = v[i]; if (scale) w = w * scale[k0 + kk]; float* d = scr + kk * 65 + lc; d[0] = w[0]; d[1] = w[1]; d[2] = w[2]; d[3] = w[3]; }
;     LDS_WAIT(); asm volatile("" ::: "memory");
;     const int c = lane & 7;
; #pragma unroll
;     for (int j = 0; j < 8; ++j) { const int n = (lane >> 3) + 8 * j; const float* sp = scr + (8 * c) * 65 + n;
;         v4u o; o.x = pk2(sp[0 * 65], sp[1 * 65]); o.y = pk2(sp[2 * 65], sp[3 * 65]); o.z = pk2(sp[4 * 65], sp[5 * 65]); o.w = pk2(sp[6 * 65], sp[7 * 65]);
;         *(v4u*)(WT + (size_t)(n0 + n) * K + k0 + 8 * c) = o; }
	ds_write2_b32 v0, v16, v17 offset1:1
	v_add_u32_e32 v0, 0x1048, v71
	ds_write2_b32 v0, v18, v19 offset1:1
	v_add_u32_e32 v0, 0x1450, v71
	s_waitcnt vmcnt(10)
	ds_write2_b32 v0, v20, v21 offset1:1
	v_add_u32_e32 v0, 0x1458, v71
	ds_write2_b32 v0, v22, v23 offset1:1
	v_add_u32_e32 v0, 0x1860, v71
	v_readlane_b32 s51, v253, 21
	v_readlane_b32 s52, v253, 22
	v_readlane_b32 s53, v253, 23
	s_waitcnt vmcnt(9)
	ds_write2_b32 v0, v24, v25 offset1:1
	v_add_u32_e32 v0, 0x1868, v71
	ds_write2_b32 v0, v26, v27 offset1:1
	v_add_u32_e32 v0, 0x1c70, v71
	s_waitcnt vmcnt(8)
	ds_write2_b32 v0, v28, v29 offset1:1
	v_add_u32_e32 v0, 0x1c78, v71
	ds_write2_b32 v0, v30, v31 offset1:1
	v_add_u32_e32 v0, 0x2080, v71
	v_readlane_b32 s54, v253, 24
	v_readlane_b32 s55, v253, 25
	v_readlane_b32 s56, v253, 26
	s_waitcnt vmcnt(7)
	ds_write2_b32 v0, v32, v33 offset1:1
	v_add_u32_e32 v0, 0x2088, v71
	ds_write2_b32 v0, v34, v35 offset1:1
	v_add_u32_e32 v0, 0x2490, v71
	s_waitcnt vmcnt(6)
	ds_write2_b32 v0, v36, v37 offset1:1
	v_add_u32_e32 v0, 0x2498, v71
	ds_write2_b32 v0, v38, v39 offset1:1
	v_add_u32_e32 v0, 0x28a0, v71
	v_readlane_b32 s57, v253, 27
	v_readlane_b32 s58, v253, 28
	v_readlane_b32 s59, v253, 29
	s_waitcnt vmcnt(5)
	ds_write2_b32 v0, v40, v41 offset1:1
	v_add_u32_e32 v0, 0x28a8, v71
	ds_write2_b32 v0, v42, v43 offset1:1
	v_add_u32_e32 v0, 0x2cb0, v71
	s_waitcnt vmcnt(4)
	ds_write2_b32 v0, v44, v45 offset1:1
	v_add_u32_e32 v0, 0x2cb8, v71
	ds_write2_b32 v0, v46, v47 offset1:1
	v_add_u32_e32 v0, 0x30c0, v71
	s_waitcnt vmcnt(3)
	ds_write2_b32 v0, v48, v49 offset1:1
	v_add_u32_e32 v0, 0x30c8, v71
	ds_write2_b32 v0, v50, v51 offset1:1
	v_add_u32_e32 v0, 0x34d0, v71
	v_readlane_b32 s60, v253, 30
	s_waitcnt vmcnt(2)
	ds_write2_b32 v0, v52, v53 offset1:1
	v_add_u32_e32 v0, 0x34d8, v71
	ds_write2_b32 v0, v54, v55 offset1:1
	v_add_u32_e32 v0, 0x38e0, v71
	v_readlane_b32 s61, v253, 31
	s_waitcnt vmcnt(1)
	ds_write2_b32 v0, v56, v57 offset1:1
	v_add_u32_e32 v0, 0x38e8, v71
	ds_write2_b32 v0, v58, v59 offset1:1
	v_add_u32_e32 v0, 0x3cf0, v71
	s_waitcnt vmcnt(0)
	ds_write2_b32 v0, v60, v61 offset1:1
	v_add_u32_e32 v0, 0x3cf8, v71
	ds_write2_b32 v0, v62, v63 offset1:1
	s_waitcnt lgkmcnt(0)
	ds_read_b32 v0, v81
	ds_read_b32 v1, v81 offset:260
	ds_read_b32 v2, v81 offset:520
	ds_read_b32 v3, v81 offset:780
	ds_read_b32 v6, v81 offset:1040
	ds_read_b32 v7, v81 offset:1300
	ds_read_b32 v8, v81 offset:1560
	ds_read_b32 v9, v81 offset:1820
	s_waitcnt lgkmcnt(6)
	v_cvt_pk_bf16_f32 v0, v0, v1
	s_waitcnt lgkmcnt(4)
	v_cvt_pk_bf16_f32 v1, v2, v3
	s_waitcnt lgkmcnt(2)
	v_cvt_pk_bf16_f32 v2, v6, v7
	v_or_b32_e32 v6, s2, v80
	v_lshlrev_b32_e32 v168, 9, v6
	v_lshl_add_u64 v[6:7], v[4:5], 0, v[168:169]
	s_waitcnt lgkmcnt(0)
	v_cvt_pk_bf16_f32 v3, v8, v9
	global_store_dwordx4 v[6:7], v[0:3], off
	ds_read_b32 v0, v81 offset:32
	ds_read_b32 v1, v81 offset:292
	ds_read_b32 v2, v81 offset:552
	ds_read_b32 v3, v81 offset:812
	ds_read_b32 v6, v81 offset:1072
	ds_read_b32 v7, v81 offset:1332
	ds_read_b32 v8, v81 offset:1592
	ds_read_b32 v9, v81 offset:1852
	s_waitcnt lgkmcnt(0)
	v_cvt_pk_bf16_f32 v0, v0, v1
	v_cvt_pk_bf16_f32 v1, v2, v3
	v_cvt_pk_bf16_f32 v2, v6, v7
	v_or_b32_e32 v6, s2, v82
	v_lshlrev_b32_e32 v168, 9, v6
	v_lshl_add_u64 v[6:7], v[4:5], 0, v[168:169]
	v_cvt_pk_bf16_f32 v3, v8, v9
	global_store_dwordx4 v[6:7], v[0:3], off
	ds_read_b32 v0, v81 offset:64
	ds_read_b32 v1, v81 offset:324
	ds_read_b32 v2, v81 offset:584
	ds_read_b32 v3, v81 offset:844
	ds_read_b32 v6, v81 offset:1104
	ds_read_b32 v7, v81 offset:1364
	ds_read_b32 v8, v81 offset:1624
	ds_read_b32 v9, v81 offset:1884
	s_waitcnt lgkmcnt(0)
	v_cvt_pk_bf16_f32 v0, v0, v1
	v_cvt_pk_bf16_f32 v1, v2, v3
	v_cvt_pk_bf16_f32 v2, v6, v7
	v_or_b32_e32 v6, s2, v83
	v_lshlrev_b32_e32 v168, 9, v6
	v_lshl_add_u64 v[6:7], v[4:5], 0, v[168:169]
	v_cvt_pk_bf16_f32 v3, v8, v9
	global_store_dwordx4 v[6:7], v[0:3], off
	ds_read_b32 v0, v81 offset:96
	ds_read_b32 v1, v81 offset:356
	ds_read_b32 v2, v81 offset:616
	ds_read_b32 v3, v81 offset:876
	ds_read_b32 v6, v81 offset:1136
	ds_read_b32 v7, v81 offset:1396
	ds_read_b32 v8, v81 offset:1656
	ds_read_b32 v9, v81 offset:1916
	s_waitcnt lgkmcnt(0)
	v_cvt_pk_bf16_f32 v0, v0, v1
	v_cvt_pk_bf16_f32 v1, v2, v3
	v_cvt_pk_bf16_f32 v2, v6, v7
	v_or_b32_e32 v6, s2, v84
	v_lshlrev_b32_e32 v168, 9, v6
	v_lshl_add_u64 v[6:7], v[4:5], 0, v[168:169]
	v_cvt_pk_bf16_f32 v3, v8, v9
	global_store_dwordx4 v[6:7], v[0:3], off
	ds_read_b32 v0, v81 offset:128
	ds_read_b32 v1, v81 offset:388
	ds_read_b32 v2, v81 offset:648
	ds_read_b32 v3, v81 offset:908
	ds_read_b32 v6, v81 offset:1168
	ds_read_b32 v7, v81 offset:1428
	ds_read_b32 v8, v81 offset:1688
	ds_read_b32 v9, v81 offset:1948
	s_waitcnt lgkmcnt(0)
	v_cvt_pk_bf16_f32 v0, v0, v1
	v_cvt_pk_bf16_f32 v1, v2, v3
	v_cvt_pk_bf16_f32 v2, v6, v7
	v_or_b32_e32 v6, s2, v85
	v_lshlrev_b32_e32 v168, 9, v6
	v_lshl_add_u64 v[6:7], v[4:5], 0, v[168:169]
	v_cvt_pk_bf16_f32 v3, v8, v9
	global_store_dwordx4 v[6:7], v[0:3], off
	ds_read_b32 v0, v81 offset:160
	ds_read_b32 v1, v81 offset:420
	ds_read_b32 v2, v81 offset:680
	ds_read_b32 v3, v81 offset:940
	ds_read_b32 v6, v81 offset:1200
	ds_read_b32 v7, v81 offset:1460
	ds_read_b32 v8, v81 offset:1720
	ds_read_b32 v9, v81 offset:1980
	s_waitcnt lgkmcnt(0)
	v_cvt_pk_bf16_f32 v0, v0, v1
	v_cvt_pk_bf16_f32 v1, v2, v3
	v_cvt_pk_bf16_f32 v2, v6, v7
	v_or_b32_e32 v6, s2, v86
	v_lshlrev_b32_e32 v168, 9, v6
	v_lshl_add_u64 v[6:7], v[4:5], 0, v[168:169]
	v_cvt_pk_bf16_f32 v3, v8, v9
	global_store_dwordx4 v[6:7], v[0:3], off
	ds_read_b32 v0, v81 offset:192
	ds_read_b32 v1, v81 offset:452
	ds_read_b32 v2, v81 offset:712
	ds_read_b32 v3, v81 offset:972
	ds_read_b32 v6, v81 offset:1232
	ds_read_b32 v7, v81 offset:1492
	ds_read_b32 v8, v81 offset:1752
	ds_read_b32 v9, v81 offset:2012
	s_waitcnt lgkmcnt(0)
	v_cvt_pk_bf16_f32 v0, v0, v1
	v_cvt_pk_bf16_f32 v1, v2, v3
	v_cvt_pk_bf16_f32 v2, v6, v7
	v_or_b32_e32 v6, s2, v87
	v_lshlrev_b32_e32 v168, 9, v6
	v_lshl_add_u64 v[6:7], v[4:5], 0, v[168:169]
	v_cvt_pk_bf16_f32 v3, v8, v9
	global_store_dwordx4 v[6:7], v[0:3], off
	ds_read_b32 v0, v81 offset:224
	ds_read_b32 v1, v81 offset:484
	ds_read_b32 v2, v81 offset:744
	ds_read_b32 v3, v81 offset:1004
	ds_read_b32 v6, v81 offset:1264
	ds_read_b32 v7, v81 offset:1524
	ds_read_b32 v8, v81 offset:1784
	ds_read_b32 v9, v81 offset:2044
	s_waitcnt lgkmcnt(0)
	v_cvt_pk_bf16_f32 v0, v0, v1
	v_cvt_pk_bf16_f32 v1, v2, v3
	v_cvt_pk_bf16_f32 v2, v6, v7
	v_or_b32_e32 v6, s2, v88
	v_lshlrev_b32_e32 v168, 9, v6
	v_lshl_add_u64 v[4:5], v[4:5], 0, v[168:169]
	v_cvt_pk_bf16_f32 v3, v8, v9
	global_store_dwordx4 v[4:5], v[0:3], off
	s_waitcnt lgkmcnt(0)
	s_mov_b64 s[2:3], 0
